# static s_setprio 1 for waves 0-3 (instead of 4-7) during the attention tile loop
# speedup vs baseline: 1.0022x; 1.0002x over previous
; __device__ __forceinline__ float bflo(unsigned u) { return __uint_as_float(u << 16); }
; __device__ __forceinline__ float bfhi(unsigned u) { return __uint_as_float(u & 0xffff0000u); }
; #define DMA_WAIT_BAR() do { asm volatile("s_waitcnt vmcnt(0)" ::: "memory"); __syncthreads(); } while (0)
; #define RD_K(slot) do { const LAS unsigned char* kp_ = L + (slot) * ASLOT; \
;         _Pragma("unroll") for (int st = 0; st < 4; ++st) { kf[2 * st] = *(const LAS bf16x8*)(kp_ + (kb0 ^ (32 * st))); kf[2 * st + 1] = *(const LAS bf16x8*)(kp_ + 8192 + (kb0 ^ (32 * st))); } } while (0)
; __device__ __forceinline__ void attn_unit(LAS unsigned char* L, bf16_t* QKV, size_t rowbase, int S, int h, int qb, float lam, const float* subln, unsigned* kmax) {
;     ...
;         const int seq = rowbase < (size_t)TP ? (int)(rowbase >> 14) : 2 + (int)((rowbase - TP) >> 13);
;         unsigned* kp = kmax + (seq * 16 + 2 * h + hd) * 2;
;         const float kb = sqrtf(__uint_as_float(__hip_atomic_load(kp, __ATOMIC_RELAXED, __HIP_MEMORY_SCOPE_AGENT)) + __uint_as_float(__hip_atomic_load(kp + 1, __ATOMIC_RELAXED, __HIP_MEMORY_SCOPE_AGENT)));
;         float q2 = 0.f;
; #pragma unroll
;         for (int st = 0; st < 4; ++st) { const u32x4 w = __builtin_bit_cast(u32x4, qf[st]);
;             q2 += ((bflo(w.x) * bflo(w.x) + bfhi(w.x) * bfhi(w.x)) + (bflo(w.y) * bflo(w.y) + bfhi(w.y) * bfhi(w.y))) + ((bflo(w.z) * bflo(w.z) + bfhi(w.z) * bfhi(w.z)) + (bflo(w.w) * bflo(w.w) + bfhi(w.w) * bfhi(w.w))); }
;         q2 += __shfl_xor(q2, 32);
;         const float mref = sqrtf(q2) * kb;
; #pragma unroll
;         for (int r = 0; r < 16; ++r) negm[r] = -mref; }
;     DMA_WAIT_BAR();
;     bf16x8 kf[8], va[4], vb[4];
;     ...
;     RD_K(0);
;     __syncthreads();
.LBB0_926:
	s_lshl_b32 s5, s63, 2
	s_lshl_b32 s10, s40, 1
	s_lshl_b32 s4, s22, 5
	s_add_i32 s5, s10, s5
	s_add_i32 s10, s5, s4
	s_lshl_b32 s23, s40, 3
	s_lshl_b64 s[4:5], s[10:11], 2
	s_add_u32 s4, s26, s4
	s_addc_u32 s5, s27, s5
	global_load_dword v25, v157, s[4:5] sc1
	global_load_dword v27, v157, s[4:5] offset:4 sc1
	s_waitcnt vmcnt(5)
	v_and_b32_e32 v3, 0xffff0000, v113
	v_and_b32_e32 v2, 0xffff0000, v112
	v_and_b32_e32 v7, 0xffff0000, v115
	v_and_b32_e32 v6, 0xffff0000, v114
	s_waitcnt vmcnt(4)
	v_and_b32_e32 v11, 0xffff0000, v117
	v_and_b32_e32 v10, 0xffff0000, v116
	v_and_b32_e32 v15, 0xffff0000, v119
	v_and_b32_e32 v14, 0xffff0000, v118
	v_lshlrev_b32_e32 v1, 16, v113
	v_lshlrev_b32_e32 v0, 16, v112
	v_lshlrev_b32_e32 v5, 16, v115
	v_lshlrev_b32_e32 v4, 16, v114
	v_lshlrev_b32_e32 v9, 16, v117
	v_lshlrev_b32_e32 v8, 16, v116
	v_lshlrev_b32_e32 v13, 16, v119
	v_lshlrev_b32_e32 v12, 16, v118
	v_pk_mul_f32 v[2:3], v[2:3], v[2:3]
	v_pk_mul_f32 v[6:7], v[6:7], v[6:7]
	v_pk_mul_f32 v[10:11], v[10:11], v[10:11]
	v_pk_mul_f32 v[14:15], v[14:15], v[14:15]
	s_waitcnt vmcnt(2)
	v_lshlrev_b32_e32 v24, 16, v124
	v_and_b32_e32 v26, 0xffff0000, v124
	v_lshlrev_b32_e32 v28, 16, v125
	v_and_b32_e32 v29, 0xffff0000, v125
	v_pk_fma_f32 v[0:1], v[0:1], v[0:1], v[2:3]
	v_pk_fma_f32 v[2:3], v[4:5], v[4:5], v[6:7]
	v_pk_fma_f32 v[4:5], v[8:9], v[8:9], v[10:11]
	v_pk_fma_f32 v[6:7], v[12:13], v[12:13], v[14:15]
	v_mul_f32_e32 v35, v24, v24
	v_mul_f32_e32 v36, v26, v26
	v_mul_f32_e32 v37, v28, v28
	v_mul_f32_e32 v29, v29, v29
	v_pk_add_f32 v[0:1], v[0:1], v[0:1] op_sel:[0,1] op_sel_hi:[1,0]
	v_pk_add_f32 v[2:3], v[2:3], v[2:3] op_sel:[0,1] op_sel_hi:[1,0]
	v_pk_add_f32 v[4:5], v[4:5], v[4:5] op_sel:[0,1] op_sel_hi:[1,0]
	v_pk_add_f32 v[6:7], v[6:7], v[6:7] op_sel:[0,1] op_sel_hi:[1,0]
	v_mov_b32_e32 v1, v35
	v_mov_b32_e32 v3, v36
	v_mov_b32_e32 v5, v37
	v_mov_b32_e32 v7, v29
	v_pk_add_f32 v[0:1], v[0:1], v[2:3]
	v_pk_add_f32 v[2:3], v[4:5], v[6:7]
	v_and_b32_e32 v17, 0xffff0000, v120
	v_and_b32_e32 v19, 0xffff0000, v121
	v_and_b32_e32 v21, 0xffff0000, v122
	v_and_b32_e32 v23, 0xffff0000, v123
	v_lshlrev_b32_e32 v30, 16, v126
	v_and_b32_e32 v31, 0xffff0000, v126
	v_pk_add_f32 v[0:1], v[0:1], v[2:3]
	v_lshlrev_b32_e32 v16, 16, v120
	v_lshlrev_b32_e32 v18, 16, v121
	v_lshlrev_b32_e32 v20, 16, v122
	v_lshlrev_b32_e32 v22, 16, v123
	v_lshlrev_b32_e32 v32, 16, v127
	v_and_b32_e32 v33, 0xffff0000, v127
	v_mul_f32_e32 v38, v30, v30
	v_mul_f32_e32 v31, v31, v31
	v_mul_f32_e32 v24, v17, v17
	v_mul_f32_e32 v26, v19, v19
	v_mul_f32_e32 v28, v21, v21
	v_mul_f32_e32 v30, v23, v23
	v_mul_f32_e32 v32, v32, v32
	v_mul_f32_e32 v33, v33, v33
	v_pk_fma_f32 v[12:13], v[20:21], v[20:21], v[28:29] op_sel_hi:[1,1,0]
	v_pk_fma_f32 v[14:15], v[22:23], v[22:23], v[30:31] op_sel_hi:[1,1,0]
	v_mov_b32_e32 v13, v32
	v_mov_b32_e32 v15, v33
	v_and_b32_e32 v6, 64, v186
	v_add_u32_e32 v6, 64, v6
	v_bitop3_b32 v34, s23, v171, v181 bitop3:0x36
	v_lshl_add_u32 v34, v34, 4, v172
	v_add_u32_e32 v188, 0, v34
	s_waitcnt vmcnt(0)
	s_barrier
; __device__ __forceinline__ float bflo(unsigned u) { return __uint_as_float(u << 16); }
; __device__ __forceinline__ float bfhi(unsigned u) { return __uint_as_float(u & 0xffff0000u); }
; #define DMA_WAIT_BAR() do { asm volatile("s_waitcnt vmcnt(0)" ::: "memory"); __syncthreads(); } while (0)
; #define RD_K(slot) do { const LAS unsigned char* kp_ = L + (slot) * ASLOT; \
;         _Pragma("unroll") for (int st = 0; st < 4; ++st) { kf[2 * st] = *(const LAS bf16x8*)(kp_ + (kb0 ^ (32 * st))); kf[2 * st + 1] = *(const LAS bf16x8*)(kp_ + 8192 + (kb0 ^ (32 * st))); } } while (0)
; __device__ __forceinline__ void attn_unit(LAS unsigned char* L, bf16_t* QKV, size_t rowbase, int S, int h, int qb, float lam, const float* subln, unsigned* kmax) {
;     ...
;         const float kb = sqrtf(__uint_as_float(__hip_atomic_load(kp, __ATOMIC_RELAXED, __HIP_MEMORY_SCOPE_AGENT)) + __uint_as_float(__hip_atomic_load(kp + 1, __ATOMIC_RELAXED, __HIP_MEMORY_SCOPE_AGENT)));
;         float q2 = 0.f;
; #pragma unroll
;         for (int st = 0; st < 4; ++st) { const u32x4 w = __builtin_bit_cast(u32x4, qf[st]);
;             q2 += ((bflo(w.x) * bflo(w.x) + bfhi(w.x) * bfhi(w.x)) + (bflo(w.y) * bflo(w.y) + bfhi(w.y) * bfhi(w.y))) + ((bflo(w.z) * bflo(w.z) + bfhi(w.z) * bfhi(w.z)) + (bflo(w.w) * bflo(w.w) + bfhi(w.w) * bfhi(w.w))); }
;         q2 += __shfl_xor(q2, 32);
;         const float mref = sqrtf(q2) * kb;
; #pragma unroll
;         for (int r = 0; r < 16; ++r) negm[r] = -mref; }
;     DMA_WAIT_BAR();
;     bf16x8 kf[8], va[4], vb[4];
;     ...
;     RD_K(0);
;     __syncthreads();
;     bf16x8 pf[4];
	ds_read_b128 v[80:83], v188
	ds_read_b128 v[128:131], v188 offset:8192
	v_mov_b32_e32 v187, 0
	s_waitcnt vmcnt(1)
	v_pk_fma_f32 v[8:9], v[16:17], v[16:17], v[24:25] op_sel_hi:[1,1,0]
	s_waitcnt vmcnt(0)
	v_add_f32_e32 v2, v27, v25
	v_mul_f32_e32 v3, 0x4f800000, v2
	v_cmp_gt_f32_e32 vcc, s37, v2
	v_pk_fma_f32 v[10:11], v[18:19], v[18:19], v[26:27] op_sel_hi:[1,1,0]
	v_mov_b32_e32 v9, v38
	v_cndmask_b32_e32 v4, v2, v3, vcc
	v_mov_b32_e32 v11, v31
	v_sqrt_f32_e32 v5, v4
	v_pk_add_f32 v[8:9], v[8:9], v[10:11]
	v_pk_add_f32 v[10:11], v[12:13], v[14:15]
	s_add_i32 s24, s42, -1
	v_pk_add_f32 v[2:3], v[8:9], v[10:11]
	s_add_i32 s25, s43, 0x1c000
	v_pk_add_f32 v[0:1], v[0:1], v[2:3]
	v_xor_b32_e32 v3, 32, v186
	v_add_f32_e32 v0, v0, v1
	v_add_u32_e32 v1, -1, v5
	v_fma_f32 v2, -v1, v5, v4
	v_cmp_ge_f32_e64 s[4:5], 0, v2
	v_add_u32_e32 v2, 1, v5
	s_add_i32 s63, s43, 0x1e000
	v_cndmask_b32_e64 v1, v5, v1, s[4:5]
	v_cmp_lt_i32_e64 s[4:5], v3, v6
	v_fma_f32 v5, -v2, v5, v4
	s_mov_b32 s68, 7
	v_cndmask_b32_e64 v3, v186, v3, s[4:5]
	v_lshlrev_b32_e32 v156, 2, v3
	ds_bpermute_b32 v3, v156, v0
	v_cmp_lt_f32_e64 s[4:5], 0, v5
	v_mov_b32_e32 v192, 0
	v_mov_b32_e32 v193, 0
	v_cndmask_b32_e64 v1, v1, v2, s[4:5]
	s_waitcnt lgkmcnt(0)
	v_add_f32_e32 v0, v0, v3
	v_mul_f32_e32 v3, 0x4f800000, v0
	v_cmp_gt_f32_e64 s[4:5], s37, v0
	v_mul_f32_e32 v2, 0x37800000, v1
	v_cndmask_b32_e32 v1, v1, v2, vcc
	v_cndmask_b32_e64 v0, v0, v3, s[4:5]
	v_sqrt_f32_e32 v3, v0
	v_cmp_class_f32_e32 vcc, v4, v173
	v_mov_b32_e32 v194, 0
	v_mov_b32_e32 v5, v187
	v_add_u32_e32 v2, -1, v3
	v_cndmask_b32_e32 v1, v1, v4, vcc
	v_fma_f32 v4, -v2, v3, v0
	v_cmp_ge_f32_e32 vcc, 0, v4
	v_add_u32_e32 v4, 1, v3
	v_mov_b32_e32 v6, v187
	v_cndmask_b32_e32 v2, v3, v2, vcc
	v_fma_f32 v3, -v4, v3, v0
	v_cmp_lt_f32_e32 vcc, 0, v3
	v_mov_b32_e32 v7, v187
	v_mov_b32_e32 v8, v187
	v_cndmask_b32_e32 v2, v2, v4, vcc
	v_mul_f32_e32 v3, 0x37800000, v2
	v_cndmask_b32_e64 v2, v2, v3, s[4:5]
	v_cmp_class_f32_e32 vcc, v0, v173
	v_mov_b32_e32 v3, v187
	v_mov_b32_e32 v4, v187
	v_cndmask_b32_e32 v0, v2, v0, vcc
	v_mul_f32_e64 v64, v0, -v1
	v_xor_b32_e32 v0, 32, v34
	v_add_u32_e32 v189, 0, v0
	v_xor_b32_e32 v0, 64, v34
	v_add_u32_e32 v190, 0, v0
	v_xor_b32_e32 v0, 0x60, v34
	v_add_u32_e32 v191, 0, v0
	ds_read_b128 v[132:135], v189
	ds_read_b128 v[136:139], v189 offset:8192
	ds_read_b128 v[140:143], v190
	ds_read_b128 v[144:147], v190 offset:8192
	ds_read_b128 v[148:151], v191
	ds_read_b128 v[152:155], v191 offset:8192
	v_mov_b32_e32 v65, v64
	v_mov_b32_e32 v66, v64
	v_mov_b32_e32 v67, v64
	v_mov_b32_e32 v68, v64
	v_mov_b32_e32 v69, v64
	v_mov_b32_e32 v70, v64
	v_mov_b32_e32 v71, v64
	v_mov_b32_e32 v72, v64
	v_mov_b32_e32 v73, v64
	v_mov_b32_e32 v74, v64
	v_mov_b32_e32 v75, v64
	v_mov_b32_e32 v76, v64
	v_mov_b32_e32 v77, v64
	v_mov_b32_e32 v78, v64
	v_mov_b32_e32 v79, v64
	v_mov_b32_e32 v0, 0
	v_mov_b32_e32 v1, v187
	v_mov_b32_e32 v2, v187
	v_mov_b32_e32 v9, v187
	v_mov_b32_e32 v10, v187
	v_mov_b32_e32 v11, v187
	v_mov_b32_e32 v12, v187
	v_mov_b32_e32 v13, v187
	v_mov_b32_e32 v14, v187
	v_mov_b32_e32 v15, v187
	v_mov_b32_e32 v16, 0
	v_mov_b32_e32 v17, v187
	v_mov_b32_e32 v18, v187
	v_mov_b32_e32 v19, v187
	v_mov_b32_e32 v20, v187
	v_mov_b32_e32 v21, v187
	v_mov_b32_e32 v22, v187
	v_mov_b32_e32 v23, v187
	v_mov_b32_e32 v24, v187
	v_mov_b32_e32 v25, v187
	v_mov_b32_e32 v26, v187
	v_mov_b32_e32 v27, v187
	v_mov_b32_e32 v28, v187
	v_mov_b32_e32 v29, v187
	v_mov_b32_e32 v30, v187
	v_mov_b32_e32 v31, v187
	v_mov_b32_e32 v32, 0
	v_mov_b32_e32 v33, v187
	v_mov_b32_e32 v34, v187
	v_mov_b32_e32 v35, v187
	v_mov_b32_e32 v36, v187
	v_mov_b32_e32 v37, v187
	v_mov_b32_e32 v38, v187
	v_mov_b32_e32 v39, v187
	v_mov_b32_e32 v40, v187
	v_mov_b32_e32 v41, v187
	v_mov_b32_e32 v42, v187
	v_mov_b32_e32 v43, v187
	v_mov_b32_e32 v44, v187
	v_mov_b32_e32 v45, v187
	v_mov_b32_e32 v46, v187
	v_mov_b32_e32 v47, v187
	v_mov_b32_e32 v48, 0
	v_mov_b32_e32 v49, v187
	v_mov_b32_e32 v50, v187
	v_mov_b32_e32 v51, v187
	v_mov_b32_e32 v52, v187
	v_mov_b32_e32 v53, v187
	v_mov_b32_e32 v54, v187
	v_mov_b32_e32 v55, v187
	v_mov_b32_e32 v56, v187
	v_mov_b32_e32 v57, v187
	v_mov_b32_e32 v58, v187
	v_mov_b32_e32 v59, v187
	v_mov_b32_e32 v60, v187
	v_mov_b32_e32 v61, v187
	v_mov_b32_e32 v62, v187
	v_mov_b32_e32 v63, v187
	s_add_u32 s22, s20, 0x10000
	s_addc_u32 s23, s21, 0
	s_add_u32 s4, s20, 0x18000
	s_addc_u32 s5, s21, 0
	ds_read_b64_tr_b16 v[224:225], v174
	ds_read_b64_tr_b16 v[226:227], v175 offset:2048
	ds_read_b64_tr_b16 v[228:229], v176
	ds_read_b64_tr_b16 v[230:231], v177 offset:2048
	ds_read_b64_tr_b16 v[232:233], v178
	ds_read_b64_tr_b16 v[234:235], v179 offset:2048
	ds_read_b64_tr_b16 v[236:237], v183
	ds_read_b64_tr_b16 v[238:239], v184 offset:2048
	v_add_u32_e32 v254, 0x4000, v163
	v_add_u32_e32 v255, 0x100, v163
	v_add_u32_e32 v253, 0x4100, v163
	s_cmp_eq_u32 s40, 0
	s_cbranch_scc0 .Lattn_noprio
	s_setprio 1
